# SWA QK: the four K-fragment ds_read_b128 of each key tile issued together into separate registers with counted lgkmcnt(3..0) waits, instead of re-using one register with a full wait per MFMA
# speedup vs baseline: 1.0007x; 1.0007x over previous
; #define LAS __attribute__((address_space(3)))
; #define MFMA32(a, b, c) __builtin_amdgcn_mfma_f32_32x32x16_bf16((a), (b), (c), 0, 0, 0)
; __device__ __forceinline__ int crow(int i, int hh) { return (i & 3) + 8 * (i >> 2) + 4 * hh; }
; __device__ __forceinline__ void swa_unit(LAS unsigned char* lds, const bf16_t* Z1, const bf16_t* VTA, const float* bias2, const float* sinks, bf16_t* OA, int b, int kvh, int qblk, int wv) {
;     ...
;         { const bf16_t* qp = Z1 + (rowbase + Q0 + q0w + r) * N1 + head * 64 + 8 * hh;
; #pragma unroll
;           for (int s = 0; s < 4; ++s) qf[s] = *(const bf16x8*)(qp + 16 * s); }
;         f32x16 o0, o1;
; #pragma unroll
;         for (int i = 0; i < 16; ++i) { o0[i] = 0.f; o1[i] = 0.f; }
;         float m = sink2, l = (hh == 0) ? 1.f : 0.f;
; #pragma unroll
;         for (int kt = 0; kt < 5; ++kt) {
;             const int kb = q0w + 32 * kt;
;             if (Q0 == 0 && kb + 31 < 128) continue;
;             f32x16 sc;
; #pragma unroll
;             for (int i = 0; i < 16; ++i) sc[i] = 0.f;
; #pragma unroll
;             for (int s = 0; s < 4; ++s) { const bf16x8 a = *(const LAS bf16x8*)(lds + (kb + r) * SK_ROW + s * 32 + hh * 16); sc = MFMA32(a, qf[s], sc); }
; #pragma unroll
;             for (int i = 0; i < 16; ++i) { const int c = crow(i, hh), dist = 128 - 32 * kt + r - c;
;                 const bool ok = (dist >= 0) && (dist < 128) && (Q0 > 0 || kb + c >= 128);
;                 sc[i] = ok ? sc[i] + bl[dist & 127] : -INFINITY; }
.LBB0_691:
	s_or_b32 s30, s16, s12
	s_ashr_i32 s31, s30, 31
	v_lshl_add_u64 v[74:75], v[66:67], 0, s[30:31]
	v_mad_u64_u32 v[2:3], s[16:17], v74, s27, v[68:69]
	v_mov_b32_e32 v0, v3
	v_mad_u64_u32 v[4:5], s[16:17], v75, s27, v[0:1]
	v_mov_b32_e32 v3, v4
	global_load_dwordx4 v[62:65], v[2:3], off
	global_load_dwordx4 v[58:61], v[2:3], off offset:32
	global_load_dwordx4 v[54:57], v[2:3], off offset:64
	global_load_dwordx4 v[50:53], v[2:3], off offset:96
	s_or_b32 s16, s30, 31
	s_cmpk_lt_i32 s16, 0x80
	s_cselect_b64 s[16:17], -1, 0
	s_and_b64 s[16:17], s[8:9], s[16:17]
	s_and_b64 vcc, exec, s[16:17]
	s_cbranch_vccnz .LBB0_757
	v_or_b32_e32 v0, s30, v71
	v_mad_u64_u32 v[22:23], s[16:17], v0, s19, v[70:71]
	ds_read_b128 v[162:165], v22
	ds_read_b128 v[166:169], v22 offset:32
	ds_read_b128 v[170:173], v22 offset:64
	ds_read_b128 v[174:177], v22 offset:96
	v_mov_b32_e32 v0, 0xff800000
	s_waitcnt vmcnt(3) lgkmcnt(3)
	v_mfma_f32_32x32x16_bf16 v[2:17], v[162:165], v[62:65], 0
	s_waitcnt vmcnt(2) lgkmcnt(2)
	v_mfma_f32_32x32x16_bf16 v[2:17], v[166:169], v[58:61], v[2:17]
	s_waitcnt vmcnt(1) lgkmcnt(1)
	v_mfma_f32_32x32x16_bf16 v[2:17], v[170:173], v[54:57], v[2:17]
	s_waitcnt vmcnt(0) lgkmcnt(0)
	v_mfma_f32_32x32x16_bf16 v[2:17], v[174:177], v[50:53], v[2:17]
	v_mov_b32_e32 v18, 0xff800000
	s_cmp_eq_u64 s[10:11], -1
	s_cbranch_scc1 .Lswa_fastk0
	s_and_saveexec_b64 s[16:17], s[36:37]
	s_cbranch_execz .LBB0_696
	v_or_b32_e32 v18, s30, v78
	v_cmp_lt_i32_e32 vcc, s3, v18
	s_or_b64 s[22:23], s[10:11], vcc
	v_mov_b32_e32 v18, 0xff800000
	s_and_saveexec_b64 vcc, s[22:23]
	s_cbranch_execz .LBB0_695
	ds_read_b32 v18, v80 offset:512
	s_waitcnt lgkmcnt(0)
	s_nop 0
	v_add_f32_e32 v18, v2, v18

; #define LAS __attribute__((address_space(3)))
; #define MFMA32(a, b, c) __builtin_amdgcn_mfma_f32_32x32x16_bf16((a), (b), (c), 0, 0, 0)
; __device__ __forceinline__ int crow(int i, int hh) { return (i & 3) + 8 * (i >> 2) + 4 * hh; }
; __device__ __forceinline__ void swa_unit(LAS unsigned char* lds, const bf16_t* Z1, const bf16_t* VTA, const float* bias2, const float* sinks, bf16_t* OA, int b, int kvh, int qblk, int wv) {
;     ...
;         for (int kt = 0; kt < 5; ++kt) {
;             const int kb = q0w + 32 * kt;
;             if (Q0 == 0 && kb + 31 < 128) continue;
;             f32x16 sc;
; #pragma unroll
;             for (int i = 0; i < 16; ++i) sc[i] = 0.f;
; #pragma unroll
;             for (int s = 0; s < 4; ++s) { const bf16x8 a = *(const LAS bf16x8*)(lds + (kb + r) * SK_ROW + s * 32 + hh * 16); sc = MFMA32(a, qf[s], sc); }
; #pragma unroll
;             for (int i = 0; i < 16; ++i) { const int c = crow(i, hh), dist = 128 - 32 * kt + r - c;
;                 const bool ok = (dist >= 0) && (dist < 128) && (Q0 > 0 || kb + c >= 128);
;                 sc[i] = ok ? sc[i] + bl[dist & 127] : -INFINITY; }
.LBB0_758:
	s_add_i32 s25, s30, 32
	s_xor_b64 s[28:29], s[28:29], -1
	s_or_b32 s16, s25, 31
	s_cmpk_lt_i32 s16, 0x80
	s_cselect_b64 s[16:17], -1, 0
	s_and_b64 s[16:17], s[8:9], s[16:17]
	s_and_b64 vcc, exec, s[16:17]
	s_cbranch_vccnz .LBB0_796
	v_or_b32_e32 v0, s25, v71
	v_mad_u64_u32 v[134:135], s[16:17], v0, s19, v[70:71]
	ds_read_b128 v[162:165], v134
	ds_read_b128 v[166:169], v134 offset:32
	ds_read_b128 v[170:173], v134 offset:64
	ds_read_b128 v[174:177], v134 offset:96
	v_or_b32_e32 v0, s25, v78
	v_cmp_lt_i32_e32 vcc, s3, v0
	s_or_b64 s[22:23], s[10:11], vcc
	v_mov_b32_e32 v129, 0xff800000
	s_waitcnt vmcnt(3) lgkmcnt(3)
	v_mfma_f32_32x32x16_bf16 v[34:49], v[162:165], v[62:65], 0
	s_waitcnt vmcnt(2) lgkmcnt(2)
	v_mfma_f32_32x32x16_bf16 v[34:49], v[166:169], v[58:61], v[34:49]
	s_waitcnt vmcnt(1) lgkmcnt(1)
	v_mfma_f32_32x32x16_bf16 v[34:49], v[170:173], v[54:57], v[34:49]
	s_waitcnt vmcnt(0) lgkmcnt(0)
	v_mfma_f32_32x32x16_bf16 v[34:49], v[174:177], v[50:53], v[34:49]
	v_mov_b32_e32 v130, 0xff800000
	s_cmp_eq_u64 s[10:11], -1
	s_cbranch_scc1 .Lswa_fast0
	s_and_saveexec_b64 s[16:17], s[22:23]
	s_cbranch_execz .LBB0_761
	ds_read_b32 v130, v80 offset:384
	s_waitcnt lgkmcnt(0)
	s_nop 6
	v_add_f32_e32 v130, v34, v130

; #define LAS __attribute__((address_space(3)))
; #define MFMA32(a, b, c) __builtin_amdgcn_mfma_f32_32x32x16_bf16((a), (b), (c), 0, 0, 0)
; __device__ __forceinline__ int crow(int i, int hh) { return (i & 3) + 8 * (i >> 2) + 4 * hh; }
; __device__ __forceinline__ void swa_unit(LAS unsigned char* lds, const bf16_t* Z1, const bf16_t* VTA, const float* bias2, const float* sinks, bf16_t* OA, int b, int kvh, int qblk, int wv) {
;     ...
;         for (int kt = 0; kt < 5; ++kt) {
;             const int kb = q0w + 32 * kt;
;             if (Q0 == 0 && kb + 31 < 128) continue;
;             f32x16 sc;
; #pragma unroll
;             for (int i = 0; i < 16; ++i) sc[i] = 0.f;
; #pragma unroll
;             for (int s = 0; s < 4; ++s) { const bf16x8 a = *(const LAS bf16x8*)(lds + (kb + r) * SK_ROW + s * 32 + hh * 16); sc = MFMA32(a, qf[s], sc); }
; #pragma unroll
;             for (int i = 0; i < 16; ++i) { const int c = crow(i, hh), dist = 128 - 32 * kt + r - c;
;                 const bool ok = (dist >= 0) && (dist < 128) && (Q0 > 0 || kb + c >= 128);
;                 sc[i] = ok ? sc[i] + bl[dist & 127] : -INFINITY; }
.LBB0_796:
	s_add_i32 s25, s30, 64
	s_or_b32 s16, s25, 31
	s_cmpk_lt_i32 s16, 0x80
	s_cselect_b64 s[16:17], -1, 0
	s_and_b64 s[16:17], s[8:9], s[16:17]
	s_and_b64 vcc, exec, s[16:17]
	s_cbranch_vccnz .LBB0_833
	v_or_b32_e32 v0, s25, v71
	v_mad_u64_u32 v[134:135], s[16:17], v0, s19, v[70:71]
	ds_read_b128 v[162:165], v134
	ds_read_b128 v[166:169], v134 offset:32
	ds_read_b128 v[170:173], v134 offset:64
	ds_read_b128 v[174:177], v134 offset:96
	v_or_b32_e32 v0, s25, v78
	v_cmp_lt_i32_e32 vcc, s3, v0
	s_or_b64 s[22:23], s[10:11], vcc
	v_mov_b32_e32 v129, 0xff800000
	s_waitcnt vmcnt(3) lgkmcnt(3)
	v_mfma_f32_32x32x16_bf16 v[34:49], v[162:165], v[62:65], 0
	s_waitcnt vmcnt(2) lgkmcnt(2)
	v_mfma_f32_32x32x16_bf16 v[34:49], v[166:169], v[58:61], v[34:49]
	s_waitcnt vmcnt(1) lgkmcnt(1)
	v_mfma_f32_32x32x16_bf16 v[34:49], v[170:173], v[54:57], v[34:49]
	s_waitcnt vmcnt(0) lgkmcnt(0)
	v_mfma_f32_32x32x16_bf16 v[34:49], v[174:177], v[50:53], v[34:49]
	v_mov_b32_e32 v130, 0xff800000
	s_cmp_eq_u64 s[10:11], -1
	s_cbranch_scc1 .Lswa_fast1
	s_and_saveexec_b64 s[16:17], s[22:23]
	s_cbranch_execz .LBB0_799
	ds_read_b32 v130, v80 offset:256
	s_waitcnt lgkmcnt(0)
	s_nop 6
	v_add_f32_e32 v130, v34, v130

; #define LAS __attribute__((address_space(3)))
; #define MFMA32(a, b, c) __builtin_amdgcn_mfma_f32_32x32x16_bf16((a), (b), (c), 0, 0, 0)
; __device__ __forceinline__ int crow(int i, int hh) { return (i & 3) + 8 * (i >> 2) + 4 * hh; }
; __device__ __forceinline__ void swa_unit(LAS unsigned char* lds, const bf16_t* Z1, const bf16_t* VTA, const float* bias2, const float* sinks, bf16_t* OA, int b, int kvh, int qblk, int wv) {
;     ...
;         for (int kt = 0; kt < 5; ++kt) {
;             const int kb = q0w + 32 * kt;
;             if (Q0 == 0 && kb + 31 < 128) continue;
;             f32x16 sc;
; #pragma unroll
;             for (int i = 0; i < 16; ++i) sc[i] = 0.f;
; #pragma unroll
;             for (int s = 0; s < 4; ++s) { const bf16x8 a = *(const LAS bf16x8*)(lds + (kb + r) * SK_ROW + s * 32 + hh * 16); sc = MFMA32(a, qf[s], sc); }
; #pragma unroll
;             for (int i = 0; i < 16; ++i) { const int c = crow(i, hh), dist = 128 - 32 * kt + r - c;
;                 const bool ok = (dist >= 0) && (dist < 128) && (Q0 > 0 || kb + c >= 128);
;                 sc[i] = ok ? sc[i] + bl[dist & 127] : -INFINITY; }
.LBB0_833:
	s_add_i32 s25, s30, 0x60
	s_or_b32 s16, s25, 31
	s_cmpk_lt_i32 s16, 0x80
	s_cselect_b64 s[16:17], -1, 0
	s_and_b64 s[16:17], s[8:9], s[16:17]
	s_and_b64 vcc, exec, s[16:17]
	s_cbranch_vccnz .LBB0_870
	v_or_b32_e32 v0, s25, v71
	v_mad_u64_u32 v[134:135], s[16:17], v0, s19, v[70:71]
	ds_read_b128 v[162:165], v134
	ds_read_b128 v[166:169], v134 offset:32
	ds_read_b128 v[170:173], v134 offset:64
	ds_read_b128 v[174:177], v134 offset:96
	v_or_b32_e32 v0, s25, v78
	v_cmp_lt_i32_e32 vcc, s3, v0
	s_or_b64 s[22:23], s[10:11], vcc
	v_mov_b32_e32 v129, 0xff800000
	s_waitcnt vmcnt(3) lgkmcnt(3)
	v_mfma_f32_32x32x16_bf16 v[34:49], v[162:165], v[62:65], 0
	s_waitcnt vmcnt(2) lgkmcnt(2)
	v_mfma_f32_32x32x16_bf16 v[34:49], v[166:169], v[58:61], v[34:49]
	s_waitcnt vmcnt(1) lgkmcnt(1)
	v_mfma_f32_32x32x16_bf16 v[34:49], v[170:173], v[54:57], v[34:49]
	s_waitcnt vmcnt(0) lgkmcnt(0)
	v_mfma_f32_32x32x16_bf16 v[34:49], v[174:177], v[50:53], v[34:49]
	v_mov_b32_e32 v130, 0xff800000
	s_cmp_eq_u64 s[10:11], -1
	s_cbranch_scc1 .Lswa_fast2
	s_and_saveexec_b64 s[16:17], s[22:23]
	s_cbranch_execz .LBB0_836
	ds_read_b32 v130, v80 offset:128
	s_waitcnt lgkmcnt(0)
	s_nop 6
	v_add_f32_e32 v130, v34, v130

; #define LAS __attribute__((address_space(3)))
; #define MFMA32(a, b, c) __builtin_amdgcn_mfma_f32_32x32x16_bf16((a), (b), (c), 0, 0, 0)
; __device__ __forceinline__ int crow(int i, int hh) { return (i & 3) + 8 * (i >> 2) + 4 * hh; }
; __device__ __forceinline__ void swa_unit(LAS unsigned char* lds, const bf16_t* Z1, const bf16_t* VTA, const float* bias2, const float* sinks, bf16_t* OA, int b, int kvh, int qblk, int wv) {
;     ...
;         for (int kt = 0; kt < 5; ++kt) {
;             const int kb = q0w + 32 * kt;
;             if (Q0 == 0 && kb + 31 < 128) continue;
;             f32x16 sc;
; #pragma unroll
;             for (int i = 0; i < 16; ++i) sc[i] = 0.f;
; #pragma unroll
;             for (int s = 0; s < 4; ++s) { const bf16x8 a = *(const LAS bf16x8*)(lds + (kb + r) * SK_ROW + s * 32 + hh * 16); sc = MFMA32(a, qf[s], sc); }
; #pragma unroll
;             for (int i = 0; i < 16; ++i) { const int c = crow(i, hh), dist = 128 - 32 * kt + r - c;
;                 const bool ok = (dist >= 0) && (dist < 128) && (Q0 > 0 || kb + c >= 128);
;                 sc[i] = ok ? sc[i] + bl[dist & 127] : -INFINITY; }
.LBB0_870:
	s_add_i32 s25, s30, 0x80
	s_or_b32 s16, s25, 31
	s_cmpk_lt_i32 s16, 0x80
	s_cselect_b64 s[16:17], -1, 0
	s_and_b64 s[16:17], s[8:9], s[16:17]
	s_and_b64 vcc, exec, s[16:17]
	s_cbranch_vccnz .LBB0_690
	v_or_b32_e32 v0, s25, v71
	v_mad_u64_u32 v[130:131], s[16:17], v0, s19, v[70:71]
	ds_read_b128 v[162:165], v130
	ds_read_b128 v[166:169], v130 offset:32
	ds_read_b128 v[170:173], v130 offset:64
	ds_read_b128 v[174:177], v130 offset:96
	v_or_b32_e32 v0, s25, v78
	s_waitcnt vmcnt(3) lgkmcnt(3)
	v_mfma_f32_32x32x16_bf16 v[34:49], v[162:165], v[62:65], 0
	s_waitcnt vmcnt(2) lgkmcnt(2)
	v_mfma_f32_32x32x16_bf16 v[34:49], v[166:169], v[58:61], v[34:49]
	s_waitcnt vmcnt(1) lgkmcnt(1)
	v_mfma_f32_32x32x16_bf16 v[34:49], v[170:173], v[54:57], v[34:49]
	s_waitcnt vmcnt(0) lgkmcnt(0)
	v_mfma_f32_32x32x16_bf16 v[34:49], v[174:177], v[50:53], v[34:49]
	v_mov_b32_e32 v50, 0xff800000
	v_mov_b32_e32 v51, 0xff800000
	s_cmp_eq_u64 s[10:11], -1
	s_cbranch_scc1 .Lswa_fastk4
	s_and_saveexec_b64 s[16:17], s[68:69]
	s_cbranch_execz .LBB0_875
	v_cmp_lt_i32_e32 vcc, s3, v0
	s_or_b64 s[22:23], s[10:11], vcc
	v_mov_b32_e32 v51, 0xff800000
	s_and_saveexec_b64 s[30:31], s[22:23]
	s_cbranch_execz .LBB0_874
	ds_read_b32 v51, v80
	s_waitcnt lgkmcnt(0)
	s_nop 0
	v_add_f32_e32 v51, v34, v51
